# GQA attention loop: softmax exponent arguments via v_pk_fma_f32 pairs (f32, same math)
# speedup vs baseline: 1.0039x; 1.0039x over previous
.LBB0_522:
	s_cmp_lt_u32 s15, s10
	s_cselect_b32 s4, 0, s10
	s_cselect_b32 s5, s40, s7
	s_lshl_b32 s4, s4, 5
	s_sub_i32 s4, s5, s4
	s_add_i32 s30, s21, s4
	s_add_i32 s4, s11, s15
	v_add_u32_e32 v66, s30, v189
	s_cmp_lt_u32 s4, s10
	v_ashrrev_i32_e32 v67, 31, v66
	s_cselect_b32 s4, 0, s10
	v_lshlrev_b64 v[66:67], 10, v[66:67]
	s_cselect_b32 s5, s40, s7
	s_lshl_b32 s4, s4, 5
	v_add_u32_e32 v228, 0xec00, v193
	v_add_u32_e32 v229, 0x4800, v192
	v_add_u32_e32 v230, 0x6c00, v192
	v_lshl_add_u64 v[66:67], v[178:179], 0, v[66:67]
	s_sub_i32 s4, s5, s4
	s_add_i32 s5, s33, s21
	s_waitcnt vmcnt(9)
	ds_write_b128 v191, v[130:133]
	s_waitcnt vmcnt(8)
	ds_write2_b64 v192, v[134:135], v[136:137] offset1:1
	s_waitcnt vmcnt(7)
	ds_write_b128 v191, v[142:145] offset:12800
	s_waitcnt vmcnt(6)
	ds_write2_b64 v228, v[138:139], v[140:141] offset1:1
	s_waitcnt vmcnt(5)
	ds_write_b128 v191, v[150:153] offset:25600
	s_waitcnt vmcnt(4)
	ds_write2_b64 v229, v[146:147], v[148:149] offset1:1
	s_waitcnt vmcnt(3)
	ds_write_b128 v191, v[158:161] offset:38400
	s_waitcnt vmcnt(2)
	ds_write2_b64 v230, v[154:155], v[156:157] offset1:1
	s_waitcnt vmcnt(1)
	ds_write_b128 v194, v[162:165] offset:256
	s_waitcnt vmcnt(0)
	ds_write_b128 v195, v[166:169] offset:256
	s_waitcnt lgkmcnt(0)
	s_barrier
	global_load_dwordx4 v[130:133], v[66:67], off
	v_lshl_add_u64 v[66:67], s[30:31], 1, v[180:181]
	s_add_i32 s30, s5, s4
	s_add_i32 s4, s4, s21
	global_load_dwordx4 v[134:137], v[66:67], off
	v_add_u32_e32 v66, s4, v201
	s_add_i32 s4, s18, s15
	s_cmp_lt_u32 s4, s10
	v_ashrrev_i32_e32 v67, 31, v66
	s_cselect_b32 s4, 0, s10
	v_lshlrev_b64 v[66:67], 10, v[66:67]
	s_cselect_b32 s5, s40, s7
	s_lshl_b32 s4, s4, 5
	v_lshl_add_u64 v[66:67], v[178:179], 0, v[66:67]
	s_sub_i32 s4, s5, s4
	s_add_i32 s5, s39, s21
	global_load_dwordx4 v[142:145], v[66:67], off
	v_lshl_add_u64 v[66:67], s[30:31], 1, v[180:181]
	s_add_i32 s30, s5, s4
	s_add_i32 s4, s4, s21
	global_load_dwordx4 v[138:141], v[66:67], off
	v_add_u32_e32 v66, s4, v199
	s_add_i32 s4, s19, s15
	s_cmp_lt_u32 s4, s10
	v_ashrrev_i32_e32 v67, 31, v66
	s_cselect_b32 s4, 0, s10
	v_lshlrev_b64 v[66:67], 10, v[66:67]
	s_cselect_b32 s5, s40, s7
	s_lshl_b32 s4, s4, 5
	v_lshl_add_u64 v[66:67], v[178:179], 0, v[66:67]
	s_sub_i32 s4, s5, s4
	s_add_i32 s5, s20, s21
	global_load_dwordx4 v[150:153], v[66:67], off
	v_lshl_add_u64 v[66:67], s[30:31], 1, v[180:181]
	s_add_i32 s30, s5, s4
	s_add_i32 s4, s4, s21
	global_load_dwordx4 v[146:149], v[66:67], off
	v_add_u32_e32 v66, s4, v200
	v_ashrrev_i32_e32 v67, 31, v66
	v_lshlrev_b64 v[66:67], 10, v[66:67]
	v_lshl_add_u64 v[66:67], v[178:179], 0, v[66:67]
	global_load_dwordx4 v[158:161], v[66:67], off
	v_lshl_add_u64 v[66:67], s[30:31], 1, v[180:181]
	v_cmp_gt_i32_e32 vcc, s10, v197
	v_mov_b32_e32 v68, s10
	global_load_dwordx4 v[154:157], v[66:67], off
	v_cndmask_b32_e64 v66, v68, 0, vcc
	v_mov_b32_e32 v69, s7
	v_mov_b32_e32 v70, s40
	v_cndmask_b32_e32 v67, v69, v70, vcc
	v_lshlrev_b32_e32 v66, 5, v66
	v_sub_u32_e32 v66, v67, v66
	v_add3_u32 v66, v198, s21, v66
	v_ashrrev_i32_e32 v67, 31, v66
	v_lshlrev_b64 v[66:67], 7, v[66:67]
	v_lshl_add_u64 v[66:67], v[182:183], 0, v[66:67]
	global_load_dwordx4 v[162:165], v[66:67], off
	v_add_u32_e32 v66, s18, v197
	v_cmp_gt_i32_e32 vcc, s10, v66
	v_mov_b32_e32 v0, v185
	v_mov_b32_e32 v235, v184
	v_cndmask_b32_e64 v66, v68, 0, vcc
	v_cndmask_b32_e32 v67, v69, v70, vcc
	v_lshlrev_b32_e32 v66, 5, v66
	v_sub_u32_e32 v66, v67, v66
	v_add3_u32 v66, v196, s21, v66
	v_ashrrev_i32_e32 v67, 31, v66
	v_lshlrev_b64 v[66:67], 7, v[66:67]
	v_lshl_add_u64 v[66:67], v[182:183], 0, v[66:67]
	global_load_dwordx4 v[166:169], v[66:67], off
	ds_read_b128 v[66:69], v190
	ds_read_b128 v[236:239], v190 offset:32
	s_waitcnt lgkmcnt(1)
	v_mfma_f32_32x32x16_bf16 v[66:81], v[66:69], v[118:121], 0
	v_add_u32_e32 v234, 0xc800, v227
	v_add_u32_e32 v231, 0xd800, v227
	s_add_i32 s21, s21, 32
	s_add_i32 s15, s15, 1
	v_add_u32_e32 v197, 1, v197
	s_cmp_lg_u32 s33, s21
	s_waitcnt lgkmcnt(0)
	v_mfma_f32_32x32x16_bf16 v[66:81], v[236:239], v[110:113], v[66:81]
	ds_read_b128 v[236:239], v190 offset:64
	s_waitcnt lgkmcnt(0)
	v_mfma_f32_32x32x16_bf16 v[66:81], v[236:239], v[106:109], v[66:81]
	ds_read_b128 v[236:239], v190 offset:96
	s_waitcnt lgkmcnt(0)
	v_mfma_f32_32x32x16_bf16 v[66:81], v[236:239], v[102:105], v[66:81]
	ds_read_b128 v[236:239], v190 offset:128
	s_waitcnt lgkmcnt(0)
	v_mfma_f32_32x32x16_bf16 v[66:81], v[236:239], v[98:101], v[66:81]
	ds_read_b128 v[236:239], v190 offset:160
	s_waitcnt lgkmcnt(0)
	v_mfma_f32_32x32x16_bf16 v[66:81], v[236:239], v[94:97], v[66:81]
	ds_read_b128 v[236:239], v190 offset:192
	s_waitcnt lgkmcnt(0)
	v_mfma_f32_32x32x16_bf16 v[66:81], v[236:239], v[90:93], v[66:81]
	ds_read_b128 v[236:239], v190 offset:224
	s_waitcnt lgkmcnt(0)
	v_mfma_f32_32x32x16_bf16 v[66:81], v[236:239], v[86:89], v[66:81]
	ds_read_b128 v[236:239], v190 offset:256
	s_waitcnt lgkmcnt(0)
	v_mfma_f32_32x32x16_bf16 v[66:81], v[236:239], v[122:125], v[66:81]
	ds_read_b128 v[236:239], v190 offset:288
	s_waitcnt lgkmcnt(0)
	v_mfma_f32_32x32x16_bf16 v[66:81], v[236:239], v[114:117], v[66:81]
	ds_read_b128 v[236:239], v190 offset:320
	s_waitcnt lgkmcnt(0)
	v_mfma_f32_32x32x16_bf16 v[66:81], v[236:239], v[126:129], v[66:81]
	ds_read_b128 v[236:239], v190 offset:352
	s_waitcnt lgkmcnt(0)
	v_mfma_f32_32x32x16_bf16 v[66:81], v[236:239], v[82:85], v[66:81]
	s_nop 11
	v_max_f32_e32 v184, v67, v67
	v_max_f32_e32 v185, v66, v66
	v_max_f32_e32 v184, v185, v184
	v_max3_f32 v184, v184, v68, v69
	v_max3_f32 v184, v184, v70, v71
	v_max3_f32 v184, v184, v72, v73
	v_max3_f32 v184, v184, v74, v75
	v_max3_f32 v184, v184, v76, v77
	v_max3_f32 v184, v184, v78, v79
	v_max3_f32 v184, v184, v80, v81
	v_mov_b32_e32 v185, v184
	s_nop 1
	v_permlane32_swap_b32 v185, v184
	s_waitcnt lgkmcnt(0)
	v_max3_f32 v185, v0, v184, v185
	v_mov_b32_e32 v184, v81
	v_pk_mul_f32 v[232:233], v[184:185], s[26:27] op_sel_hi:[1,0]
	v_sub_f32_e32 v0, v0, v185
	v_pk_fma_f32 v[66:67], v[66:67], s[26:27], v[232:233] op_sel:[0,0,1] op_sel_hi:[1,0,1] neg_lo:[0,0,1] neg_hi:[0,0,1]
	v_exp_f32_e32 v66, v66
	v_exp_f32_e32 v67, v67
	v_pk_fma_f32 v[68:69], v[68:69], s[26:27], v[232:233] op_sel:[0,0,1] op_sel_hi:[1,0,1] neg_lo:[0,0,1] neg_hi:[0,0,1]
	v_exp_f32_e32 v68, v68
	v_exp_f32_e32 v69, v69
	v_pk_fma_f32 v[70:71], v[70:71], s[26:27], v[232:233] op_sel:[0,0,1] op_sel_hi:[1,0,1] neg_lo:[0,0,1] neg_hi:[0,0,1]
	v_exp_f32_e32 v70, v70
	v_add_f32_e32 v184, 0, v66
	v_exp_f32_e32 v71, v71
	v_pk_fma_f32 v[72:73], v[72:73], s[26:27], v[232:233] op_sel:[0,0,1] op_sel_hi:[1,0,1] neg_lo:[0,0,1] neg_hi:[0,0,1]
	v_add_f32_e32 v184, v67, v184
	v_exp_f32_e32 v72, v72
	v_add_f32_e32 v184, v68, v184
	v_exp_f32_e32 v73, v73
	v_pk_fma_f32 v[74:75], v[74:75], s[26:27], v[232:233] op_sel:[0,0,1] op_sel_hi:[1,0,1] neg_lo:[0,0,1] neg_hi:[0,0,1]
	v_add_f32_e32 v184, v69, v184
	v_exp_f32_e32 v74, v74
	v_add_f32_e32 v184, v70, v184
	v_exp_f32_e32 v75, v75
	v_pk_fma_f32 v[76:77], v[76:77], s[26:27], v[232:233] op_sel:[0,0,1] op_sel_hi:[1,0,1] neg_lo:[0,0,1] neg_hi:[0,0,1]
	v_add_f32_e32 v184, v71, v184
	v_exp_f32_e32 v76, v76
	v_add_f32_e32 v184, v72, v184
	v_exp_f32_e32 v77, v77
	v_pk_fma_f32 v[78:79], v[78:79], s[26:27], v[232:233] op_sel:[0,0,1] op_sel_hi:[1,0,1] neg_lo:[0,0,1] neg_hi:[0,0,1]
	v_add_f32_e32 v184, v73, v184
	v_exp_f32_e32 v78, v78
	v_add_f32_e32 v184, v74, v184
	v_exp_f32_e32 v79, v79
	v_fma_f32 v80, v80, s26, -v233
	v_add_f32_e32 v184, v75, v184
	v_exp_f32_e32 v80, v80
	v_sub_f32_e32 v81, v232, v233
	v_add_f32_e32 v184, v76, v184
	v_exp_f32_e32 v81, v81
	v_add_f32_e32 v184, v77, v184
	v_add_f32_e32 v184, v78, v184
	v_mul_f32_e32 v0, 0x3dd53b94, v0
	v_add_f32_e32 v184, v79, v184
	v_exp_f32_e32 v0, v0
	v_add_f32_e32 v184, v80, v184
	v_add_f32_e32 v184, v81, v184
	v_cvt_pk_bf16_f32 v66, v66, v67
	v_cvt_pk_bf16_f32 v67, v68, v69
	v_cvt_pk_bf16_f32 v68, v70, v71
	v_cvt_pk_bf16_f32 v69, v72, v73
	v_cvt_pk_bf16_f32 v70, v74, v75
	v_cvt_pk_bf16_f32 v71, v76, v77
	v_cvt_pk_bf16_f32 v72, v78, v79
	v_cvt_pk_bf16_f32 v73, v80, v81
	ds_read2_b64 v[74:77], v234 offset1:2
	ds_read2_b64 v[78:81], v234 offset0:4 offset1:6
	v_pk_mul_f32 v[16:17], v[16:17], v[0:1] op_sel_hi:[1,0]
	v_pk_mul_f32 v[14:15], v[14:15], v[0:1] op_sel_hi:[1,0]
	v_pk_mul_f32 v[12:13], v[12:13], v[0:1] op_sel_hi:[1,0]
	v_pk_mul_f32 v[10:11], v[10:11], v[0:1] op_sel_hi:[1,0]
	v_pk_mul_f32 v[8:9], v[8:9], v[0:1] op_sel_hi:[1,0]
	v_pk_mul_f32 v[6:7], v[6:7], v[0:1] op_sel_hi:[1,0]
	v_pk_mul_f32 v[4:5], v[4:5], v[0:1] op_sel_hi:[1,0]
	v_pk_mul_f32 v[2:3], v[2:3], v[0:1] op_sel_hi:[1,0]
	v_add_u32_e32 v233, 0xd000, v227
	v_pk_mul_f32 v[48:49], v[48:49], v[0:1] op_sel_hi:[1,0]
	s_waitcnt lgkmcnt(1)
	v_mfma_f32_32x32x16_bf16 v[2:17], v[74:77], v[66:69], v[2:17]
	ds_read2_b64 v[74:77], v233 offset0:32 offset1:34
	v_mul_f32_e64 v46, v46, v0
	v_mul_f32_e64 v47, v47, v0
	v_mul_f32_e64 v44, v44, v0
	v_mul_f32_e64 v45, v45, v0
	v_pk_mul_f32 v[42:43], v[42:43], v[0:1] op_sel_hi:[1,0]
	v_pk_mul_f32 v[40:41], v[40:41], v[0:1] op_sel_hi:[1,0]
	v_pk_mul_f32 v[38:39], v[38:39], v[0:1] op_sel_hi:[1,0]
	v_pk_mul_f32 v[36:37], v[36:37], v[0:1] op_sel_hi:[1,0]
	v_pk_mul_f32 v[34:35], v[34:35], v[0:1] op_sel_hi:[1,0]
	v_pk_mul_f32 v[64:65], v[64:65], v[0:1] op_sel_hi:[1,0]
	v_pk_mul_f32 v[62:63], v[62:63], v[0:1] op_sel_hi:[1,0]
	s_waitcnt lgkmcnt(0)
	v_mfma_f32_32x32x16_bf16 v[34:49], v[74:77], v[66:69], v[34:49]
	ds_read2_b64 v[74:77], v233 offset0:36 offset1:38
	v_mul_f32_e64 v60, v60, v0
	v_mul_f32_e64 v61, v61, v0
	v_mul_f32_e64 v58, v58, v0
	v_mul_f32_e64 v59, v59, v0
	v_pk_mul_f32 v[56:57], v[56:57], v[0:1] op_sel_hi:[1,0]
	v_pk_mul_f32 v[54:55], v[54:55], v[0:1] op_sel_hi:[1,0]
	v_pk_mul_f32 v[52:53], v[52:53], v[0:1] op_sel_hi:[1,0]
	v_pk_mul_f32 v[50:51], v[50:51], v[0:1] op_sel_hi:[1,0]
	s_waitcnt lgkmcnt(0)
	v_mfma_f32_32x32x16_bf16 v[34:49], v[74:77], v[70:73], v[34:49]
	ds_read2_b64 v[74:77], v231 offset0:64 offset1:66
	v_add_u32_e32 v232, 0xe000, v227
	v_mul_f32_e64 v32, v32, v0
	v_mul_f32_e64 v33, v33, v0
	v_mul_f32_e64 v30, v30, v0
	v_mul_f32_e64 v31, v31, v0
	v_pk_mul_f32 v[28:29], v[28:29], v[0:1] op_sel_hi:[1,0]
	v_pk_mul_f32 v[26:27], v[26:27], v[0:1] op_sel_hi:[1,0]
	v_pk_mul_f32 v[24:25], v[24:25], v[0:1] op_sel_hi:[1,0]
	s_waitcnt lgkmcnt(0)
	v_mfma_f32_32x32x16_bf16 v[50:65], v[74:77], v[66:69], v[50:65]
	ds_read2_b64 v[74:77], v231 offset0:68 offset1:70
	v_mul_f32_e64 v22, v22, v0
	v_mul_f32_e64 v23, v23, v0
	v_mul_f32_e64 v20, v20, v0
	v_mul_f32_e64 v21, v21, v0
	v_pk_mul_f32 v[18:19], v[18:19], v[0:1] op_sel_hi:[1,0]
	v_fmac_f32_e32 v184, v235, v0
	s_waitcnt lgkmcnt(0)
	v_mfma_f32_32x32x16_bf16 v[50:65], v[74:77], v[70:73], v[50:65]
	ds_read2_b64 v[74:77], v232 offset0:96 offset1:98
	s_waitcnt lgkmcnt(0)
	v_mfma_f32_32x32x16_bf16 v[18:33], v[74:77], v[66:69], v[18:33]
	ds_read2_b64 v[66:69], v232 offset0:100 offset1:102
	s_waitcnt lgkmcnt(0)
	s_barrier
	v_mfma_f32_32x32x16_bf16 v[2:17], v[78:81], v[70:73], v[2:17]
	v_mfma_f32_32x32x16_bf16 v[18:33], v[66:69], v[70:73], v[18:33]
	s_cbranch_scc1 .LBB0_522
	s_waitcnt vmcnt(9)
	ds_write_b128 v191, v[130:133]
	s_waitcnt vmcnt(8)
	ds_write2_b64 v192, v[134:135], v[136:137] offset1:1
	s_waitcnt vmcnt(7)
	ds_write_b128 v191, v[142:145] offset:12800
	s_waitcnt vmcnt(6)
	ds_write2_b64 v228, v[138:139], v[140:141] offset1:1
	s_waitcnt vmcnt(5)
	ds_write_b128 v191, v[150:153] offset:25600
	s_waitcnt vmcnt(4)
	ds_write2_b64 v229, v[146:147], v[148:149] offset1:1
	s_waitcnt vmcnt(3)
	ds_write_b128 v191, v[158:161] offset:38400
	s_waitcnt vmcnt(2)
	ds_write2_b64 v230, v[154:155], v[156:157] offset1:1
	s_waitcnt vmcnt(1)
	ds_write_b128 v194, v[162:165] offset:256
	s_waitcnt vmcnt(0)
	ds_write_b128 v195, v[166:169] offset:256
	s_waitcnt lgkmcnt(0)
	s_barrier
	ds_read_b128 v[66:69], v190
	ds_read_b128 v[130:133], v190 offset:32
	s_waitcnt lgkmcnt(1)
	v_mfma_f32_32x32x16_bf16 v[66:81], v[66:69], v[118:121], 0
	v_readlane_b32 s4, v253, 17
	s_mov_b32 s7, 0xf149f2ca
	s_mov_b32 s39, s31
	s_waitcnt lgkmcnt(0)
	v_mfma_f32_32x32x16_bf16 v[66:81], v[130:133], v[110:113], v[66:81]
	ds_read_b128 v[110:113], v190 offset:64
	ds_read_b128 v[118:121], v190 offset:96
	s_waitcnt lgkmcnt(1)
	v_mfma_f32_32x32x16_bf16 v[66:81], v[110:113], v[106:109], v[66:81]
	v_ashrrev_i32_e32 v110, 6, v188
	s_waitcnt lgkmcnt(0)
	v_mfma_f32_32x32x16_bf16 v[66:81], v[118:121], v[102:105], v[66:81]
	ds_read_b128 v[102:105], v190 offset:128
	ds_read_b128 v[106:109], v190 offset:160
	s_waitcnt lgkmcnt(1)
	v_mfma_f32_32x32x16_bf16 v[66:81], v[102:105], v[98:101], v[66:81]
	s_waitcnt lgkmcnt(0)
	v_mfma_f32_32x32x16_bf16 v[66:81], v[106:109], v[94:97], v[66:81]
	ds_read_b128 v[94:97], v190 offset:192
	ds_read_b128 v[98:101], v190 offset:224
	s_waitcnt lgkmcnt(1)
	v_mfma_f32_32x32x16_bf16 v[66:81], v[94:97], v[90:93], v[66:81]
	s_waitcnt lgkmcnt(0)
	v_mfma_f32_32x32x16_bf16 v[66:81], v[98:101], v[86:89], v[66:81]
	ds_read_b128 v[86:89], v190 offset:256
	ds_read_b128 v[90:93], v190 offset:288
	s_waitcnt lgkmcnt(1)
	v_mfma_f32_32x32x16_bf16 v[66:81], v[86:89], v[122:125], v[66:81]
	s_waitcnt lgkmcnt(0)
	v_mfma_f32_32x32x16_bf16 v[66:81], v[90:93], v[114:117], v[66:81]
	ds_read_b128 v[90:93], v190 offset:320
	ds_read_b128 v[86:89], v190 offset:352
	s_waitcnt lgkmcnt(1)
	v_mfma_f32_32x32x16_bf16 v[66:81], v[90:93], v[126:129], v[66:81]
	ds_read2_b64 v[90:93], v234 offset1:2
	ds_read2_b64 v[94:97], v234 offset0:4 offset1:6
	ds_read2_b64 v[98:101], v233 offset0:32 offset1:34
	s_waitcnt lgkmcnt(3)
	v_mfma_f32_32x32x16_bf16 v[66:81], v[86:89], v[82:85], v[66:81]
	ds_read2_b64 v[84:87], v233 offset0:36 offset1:38
	ds_read2_b64 v[102:105], v231 offset0:64 offset1:66
	s_nop 9
	v_max_f32_e32 v0, v67, v67
	v_max_f32_e32 v82, v66, v66
	v_max_f32_e32 v0, v82, v0
	v_max3_f32 v0, v0, v68, v69
	v_max3_f32 v0, v0, v70, v71
	v_max3_f32 v0, v0, v72, v73
	v_max3_f32 v0, v0, v74, v75
	v_max3_f32 v0, v0, v76, v77
	v_max3_f32 v0, v0, v78, v79
	v_max3_f32 v0, v0, v80, v81
	v_mov_b32_e32 v83, v0
	v_mov_b32_e32 v88, v81
	v_and_b32_e32 v82, 1, v110
	v_permlane32_swap_b32 v83, v0
	s_waitcnt lgkmcnt(0)
	v_max3_f32 v89, v185, v0, v83
	v_sub_f32_e32 v0, v185, v89
	v_pk_mul_f32 v[106:107], v[88:89], s[26:27] op_sel_hi:[1,0]
	v_mul_f32_e32 v0, 0x3dd53b94, v0
	v_fma_f32 v66, v66, s26, -v107
	v_fma_f32 v67, v67, s26, -v107
	v_fma_f32 v68, v68, s26, -v107
	v_fma_f32 v69, v69, s26, -v107
	v_fma_f32 v70, v70, s26, -v107
	v_fma_f32 v71, v71, s26, -v107
	v_fma_f32 v72, v72, s26, -v107
	v_fma_f32 v73, v73, s26, -v107
	v_exp_f32_e32 v0, v0
	v_exp_f32_e32 v88, v66
	v_exp_f32_e32 v111, v67
	v_exp_f32_e32 v112, v68
	v_exp_f32_e32 v113, v69
	v_exp_f32_e32 v114, v70
	v_exp_f32_e32 v115, v71
	v_exp_f32_e32 v116, v72
	v_exp_f32_e32 v117, v73
	v_fma_f32 v74, v74, s26, -v107
	v_fma_f32 v75, v75, s26, -v107
	v_fma_f32 v76, v76, s26, -v107
	v_fma_f32 v77, v77, s26, -v107
	v_fma_f32 v78, v78, s26, -v107
	v_fma_f32 v79, v79, s26, -v107
	v_fma_f32 v80, v80, s26, -v107
	v_sub_f32_e32 v83, v106, v107
	v_exp_f32_e32 v118, v74
	v_exp_f32_e32 v119, v75
	v_exp_f32_e32 v120, v76
	v_exp_f32_e32 v121, v77
	v_exp_f32_e32 v122, v78
	v_exp_f32_e32 v123, v79
	v_exp_f32_e32 v124, v80
	v_pk_mul_f32 v[80:81], v[16:17], v[0:1] op_sel_hi:[1,0]
	v_pk_mul_f32 v[78:79], v[14:15], v[0:1] op_sel_hi:[1,0]
	v_pk_mul_f32 v[76:77], v[12:13], v[0:1] op_sel_hi:[1,0]
	v_pk_mul_f32 v[74:75], v[10:11], v[0:1] op_sel_hi:[1,0]
	v_pk_mul_f32 v[72:73], v[8:9], v[0:1] op_sel_hi:[1,0]
	v_pk_mul_f32 v[70:71], v[6:7], v[0:1] op_sel_hi:[1,0]
	v_pk_mul_f32 v[68:69], v[4:5], v[0:1] op_sel_hi:[1,0]
	v_pk_mul_f32 v[66:67], v[2:3], v[0:1] op_sel_hi:[1,0]
	v_pk_mul_f32 v[16:17], v[48:49], v[0:1] op_sel_hi:[1,0]
	v_cvt_pk_bf16_f32 v106, v88, v111
	v_cvt_pk_bf16_f32 v107, v112, v113
	v_cvt_pk_bf16_f32 v108, v114, v115
	v_cvt_pk_bf16_f32 v109, v116, v117
	v_pk_mul_f32 v[14:15], v[46:47], v[0:1] op_sel_hi:[1,0]
	v_pk_mul_f32 v[12:13], v[44:45], v[0:1] op_sel_hi:[1,0]
	v_pk_mul_f32 v[10:11], v[42:43], v[0:1] op_sel_hi:[1,0]
	v_pk_mul_f32 v[8:9], v[40:41], v[0:1] op_sel_hi:[1,0]
	v_pk_mul_f32 v[6:7], v[38:39], v[0:1] op_sel_hi:[1,0]
	v_pk_mul_f32 v[4:5], v[36:37], v[0:1] op_sel_hi:[1,0]
	v_pk_mul_f32 v[2:3], v[34:35], v[0:1] op_sel_hi:[1,0]
	v_pk_mul_f32 v[48:49], v[64:65], v[0:1] op_sel_hi:[1,0]
	v_pk_mul_f32 v[46:47], v[62:63], v[0:1] op_sel_hi:[1,0]
	v_pk_mul_f32 v[44:45], v[60:61], v[0:1] op_sel_hi:[1,0]
	v_pk_mul_f32 v[42:43], v[58:59], v[0:1] op_sel_hi:[1,0]
	v_pk_mul_f32 v[40:41], v[56:57], v[0:1] op_sel_hi:[1,0]
	v_pk_mul_f32 v[38:39], v[54:55], v[0:1] op_sel_hi:[1,0]
	v_pk_mul_f32 v[36:37], v[52:53], v[0:1] op_sel_hi:[1,0]
	v_pk_mul_f32 v[34:35], v[50:51], v[0:1] op_sel_hi:[1,0]
	ds_read2_b64 v[50:53], v231 offset0:68 offset1:70
	v_add_f32_e32 v54, 0, v88
	v_mfma_f32_32x32x16_bf16 v[34:49], v[102:105], v[106:109], v[34:49]
	v_add_f32_e32 v54, v111, v54
	v_exp_f32_e32 v83, v83
	v_add_f32_e32 v54, v112, v54
	v_add_f32_e32 v54, v113, v54
	v_add_f32_e32 v58, v114, v54
	ds_read2_b64 v[54:57], v232 offset0:96 offset1:98
	v_cvt_pk_bf16_f32 v62, v118, v119
	v_cvt_pk_bf16_f32 v63, v120, v121
	v_cvt_pk_bf16_f32 v64, v122, v123
	v_cvt_pk_bf16_f32 v65, v124, v83
	v_mfma_f32_32x32x16_bf16 v[66:81], v[90:93], v[106:109], v[66:81]
	v_mul_f32_e64 v32, v32, v0
	v_mul_f32_e64 v33, v33, v0
	v_mul_f32_e64 v30, v30, v0
	v_mul_f32_e64 v31, v31, v0
	v_mul_f32_e64 v28, v28, v0
	v_mul_f32_e64 v29, v29, v0
	v_pk_mul_f32 v[26:27], v[26:27], v[0:1] op_sel_hi:[1,0]
	v_pk_mul_f32 v[24:25], v[24:25], v[0:1] op_sel_hi:[1,0]
	v_pk_mul_f32 v[22:23], v[22:23], v[0:1] op_sel_hi:[1,0]
	v_pk_mul_f32 v[20:21], v[20:21], v[0:1] op_sel_hi:[1,0]
	s_waitcnt lgkmcnt(1)
	v_mfma_f32_32x32x16_bf16 v[34:49], v[50:53], v[62:65], v[34:49]
	v_add_f32_e32 v50, v115, v58
	v_add_f32_e32 v50, v116, v50
	v_add_f32_e32 v50, v117, v50
	v_add_f32_e32 v50, v118, v50
	v_add_f32_e32 v50, v119, v50
	v_pk_mul_f32 v[18:19], v[18:19], v[0:1] op_sel_hi:[1,0]
	v_add_f32_e32 v58, v120, v50
	ds_read2_b64 v[50:53], v232 offset0:100 offset1:102
	s_waitcnt lgkmcnt(1)
	v_mfma_f32_32x32x16_bf16 v[18:33], v[54:57], v[106:109], v[18:33]
	v_add_f32_e32 v54, v121, v58
	v_add_f32_e32 v54, v122, v54
	v_add_f32_e32 v54, v123, v54
	v_add_f32_e32 v54, v124, v54
	v_add_f32_e32 v54, v83, v54
	v_fmac_f32_e32 v54, v184, v0
	v_mov_b32_e32 v0, v54
	v_mfma_f32_32x32x16_bf16 v[2:17], v[98:101], v[106:109], v[2:17]
	s_nop 1
	v_permlane32_swap_b32 v0, v54
	s_waitcnt lgkmcnt(0)
	s_barrier
	v_add_f32_e32 v0, v54, v0
	v_mfma_f32_32x32x16_bf16 v[66:81], v[94:97], v[62:65], v[66:81]
	v_mfma_f32_32x32x16_bf16 v[18:33], v[50:53], v[62:65], v[18:33]
	v_lshlrev_b32_e32 v50, 9, v110
	v_lshlrev_b32_e32 v51, 2, v186
	v_add3_u32 v50, s4, v50, v51
	ds_write2st64_b32 v50, v89, v0 offset1:1
	v_lshlrev_b32_e32 v0, 14, v110
	v_add3_u32 v0, 0, v0, v51
	v_mfma_f32_32x32x16_bf16 v[2:17], v[84:87], v[62:65], v[2:17]
	s_nop 3
	ds_write2st64_b32 v0, v66, v67 offset1:1
	ds_write2st64_b32 v0, v68, v69 offset0:2 offset1:3
	ds_write2st64_b32 v0, v70, v71 offset0:4 offset1:5
	ds_write2st64_b32 v0, v72, v73 offset0:6 offset1:7
	ds_write2st64_b32 v0, v74, v75 offset0:8 offset1:9
	ds_write2st64_b32 v0, v76, v77 offset0:10 offset1:11
	ds_write2st64_b32 v0, v78, v79 offset0:12 offset1:13
	ds_write2st64_b32 v0, v80, v81 offset0:14 offset1:15
	ds_write2st64_b32 v0, v2, v3 offset0:16 offset1:17
	ds_write2st64_b32 v0, v4, v5 offset0:18 offset1:19
	ds_write2st64_b32 v0, v6, v7 offset0:20 offset1:21
	ds_write2st64_b32 v0, v8, v9 offset0:22 offset1:23
	ds_write2st64_b32 v0, v10, v11 offset0:24 offset1:25
	ds_write2st64_b32 v0, v12, v13 offset0:26 offset1:27
	ds_write2st64_b32 v0, v14, v15 offset0:28 offset1:29
	ds_write2st64_b32 v0, v16, v17 offset0:30 offset1:31
	ds_write2st64_b32 v0, v34, v35 offset0:32 offset1:33
	ds_write2st64_b32 v0, v36, v37 offset0:34 offset1:35
	ds_write2st64_b32 v0, v38, v39 offset0:36 offset1:37
	ds_write2st64_b32 v0, v40, v41 offset0:38 offset1:39
	ds_write2st64_b32 v0, v42, v43 offset0:40 offset1:41
	ds_write2st64_b32 v0, v44, v45 offset0:42 offset1:43
	ds_write2st64_b32 v0, v46, v47 offset0:44 offset1:45
	ds_write2st64_b32 v0, v48, v49 offset0:46 offset1:47
	ds_write2st64_b32 v0, v18, v19 offset0:48 offset1:49
	ds_write2st64_b32 v0, v20, v21 offset0:50 offset1:51
	ds_write2st64_b32 v0, v22, v23 offset0:52 offset1:53
	ds_write2st64_b32 v0, v24, v25 offset0:54 offset1:55
	ds_write2st64_b32 v0, v26, v27 offset0:56 offset1:57
	ds_write2st64_b32 v0, v28, v29 offset0:58 offset1:59
	ds_write2st64_b32 v0, v30, v31 offset0:60 offset1:61
	ds_write2st64_b32 v0, v32, v33 offset0:62 offset1:63
	v_lshlrev_b32_e32 v0, 9, v82
	v_add3_u32 v0, s4, v0, v51
	s_waitcnt lgkmcnt(0)
	s_barrier
	ds_read2st64_b32 v[4:5], v0 offset1:1
	ds_read2st64_b32 v[6:7], v0 offset0:4 offset1:5
	ds_read2st64_b32 v[8:9], v0 offset0:8 offset1:9
	ds_read2st64_b32 v[10:11], v0 offset0:12 offset1:13
	s_lshl_b64 s[4:5], s[38:39], 11
	s_waitcnt lgkmcnt(2)
	v_max3_f32 v0, v4, s7, v6
	s_add_u32 s7, s80, s4
	s_waitcnt lgkmcnt(0)
	v_max3_f32 v0, v0, v8, v10
	v_sub_f32_e32 v2, v4, v0
	v_mul_f32_e32 v2, 0x3dd53b94, v2
	v_exp_f32_e32 v3, v2
	v_sub_f32_e32 v2, v6, v0
	v_mul_f32_e32 v2, 0x3dd53b94, v2
	v_exp_f32_e32 v2, v2
	v_mov_b32_e32 v4, v7
	s_addc_u32 s10, s81, s5
	v_pk_mul_f32 v[6:7], v[4:5], v[2:3]
	v_sub_f32_e32 v4, v8, v0
	v_sub_f32_e32 v0, v10, v0
	v_mul_f32_e32 v4, 0x3dd53b94, v4
	v_mul_f32_e32 v0, 0x3dd53b94, v0
	v_exp_f32_e32 v5, v4
	v_exp_f32_e32 v4, v0
	v_add_f32_e32 v0, 0, v7
	v_mov_b32_e32 v8, v11
	v_add_f32_e32 v0, v6, v0
	v_pk_mul_f32 v[6:7], v[8:9], v[4:5]
	s_nop 0
	v_add_f32_e32 v0, v7, v0
	v_add_f32_e32 v0, v6, v0
	v_div_scale_f32 v6, s[4:5], v0, v0, 1.0
	v_rcp_f32_e32 v7, v6
	s_lshl_b32 s4, s14, 1
	s_add_u32 s38, s7, s4
	s_addc_u32 s39, s10, 0
	v_fma_f32 v8, -v6, v7, 1.0
	v_fmac_f32_e32 v7, v8, v7
	v_div_scale_f32 v8, vcc, 1.0, v0, 1.0
	v_mul_f32_e32 v9, v8, v7
	v_fma_f32 v10, -v6, v9, v8
	v_fmac_f32_e32 v9, v10, v7
	v_fma_f32 v6, -v6, v9, v8
	v_div_fmas_f32 v6, v6, v7, v9
	v_div_fixup_f32 v0, v6, v0, 1.0
	v_lshl_add_u32 v6, v82, 14, 0
	v_lshlrev_b32_e32 v7, 12, v177
	v_add3_u32 v7, v6, v7, v51
	ds_read2st64_b32 v[8:9], v7 offset1:1
	ds_read2st64_b32 v[10:11], v7 offset0:128 offset1:129
	v_mov_b32_e32 v6, v3
	v_add_u32_e32 v24, 0x10000, v7
	v_add_u32_e32 v25, 0x18000, v7
	v_add_u32_e32 v27, 0x10100, v7
	v_add_u32_e32 v28, 0x18100, v7
	ds_read2st64_b32 v[12:13], v7 offset0:2 offset1:3
	ds_read2st64_b32 v[14:15], v7 offset0:4 offset1:5
	ds_read2st64_b32 v[16:17], v7 offset0:6 offset1:7
	s_waitcnt lgkmcnt(4)
	v_pk_fma_f32 v[8:9], v[8:9], v[6:7], 0 op_sel_hi:[1,0,0]
	v_add_u32_e32 v31, 0x18300, v7
	ds_read2st64_b32 v[18:19], v7 offset0:130 offset1:131
	ds_read2st64_b32 v[20:21], v7 offset0:132 offset1:133
	ds_read2st64_b32 v[22:23], v7 offset0:134 offset1:135
	s_waitcnt lgkmcnt(6)
	v_pk_fma_f32 v[8:9], v[10:11], v[2:3], v[8:9] op_sel_hi:[1,0,1]
	v_mov_b32_e32 v10, v5
	v_add_u32_e32 v3, 0x10200, v7
	v_add_u32_e32 v5, 0x18200, v7
	v_add_u32_e32 v11, 0x10300, v7
	ds_read_b32 v24, v24
	ds_read_b32 v26, v25
	ds_read_b32 v25, v27
	ds_read_b32 v27, v28
	ds_read_b32 v28, v3
	ds_read_b32 v30, v5
	ds_read_b32 v29, v11
	ds_read_b32 v31, v31
	s_waitcnt lgkmcnt(13)
	v_pk_fma_f32 v[12:13], v[6:7], v[12:13], 0 op_sel_hi:[0,1,0]
	s_waitcnt lgkmcnt(5)
	v_pk_fma_f32 v[8:9], v[10:11], v[24:25], v[8:9] op_sel_hi:[0,1,1]
	v_pk_fma_f32 v[12:13], v[2:3], v[18:19], v[12:13] op_sel_hi:[0,1,1]
	v_add_u32_e32 v3, 0x10400, v7
	v_pk_fma_f32 v[14:15], v[6:7], v[14:15], 0 op_sel_hi:[0,1,0]
	s_waitcnt lgkmcnt(4)
	v_pk_fma_f32 v[8:9], v[4:5], v[26:27], v[8:9] op_sel_hi:[0,1,1]
	s_waitcnt lgkmcnt(1)
	v_pk_fma_f32 v[12:13], v[10:11], v[28:29], v[12:13] op_sel_hi:[0,1,1]
	v_add_u32_e32 v11, 0x10500, v7
	v_add_u32_e32 v24, 0x18500, v7
	v_pk_fma_f32 v[14:15], v[2:3], v[20:21], v[14:15] op_sel_hi:[0,1,1]
	v_add_u32_e32 v25, 0x10600, v7
	v_add_u32_e32 v26, 0x18600, v7
	v_add_u32_e32 v27, 0x10700, v7
	s_waitcnt lgkmcnt(0)
	v_pk_fma_f32 v[12:13], v[4:5], v[30:31], v[12:13] op_sel_hi:[0,1,1]
	v_add_u32_e32 v5, 0x18400, v7
	v_add_u32_e32 v28, 0x18700, v7
	ds_read_b32 v18, v3
	ds_read_b32 v20, v5
	ds_read_b32 v19, v11
	ds_read_b32 v21, v24
	ds_read_b32 v24, v25
	ds_read_b32 v26, v26
	ds_read_b32 v25, v27
	ds_read_b32 v27, v28
	s_waitcnt lgkmcnt(5)
	v_pk_fma_f32 v[14:15], v[10:11], v[18:19], v[14:15] op_sel_hi:[0,1,1]
	s_waitcnt lgkmcnt(4)
	v_pk_fma_f32 v[14:15], v[4:5], v[20:21], v[14:15] op_sel_hi:[0,1,1]
	ds_read2st64_b32 v[18:19], v7 offset0:8 offset1:9
	ds_read2st64_b32 v[20:21], v7 offset0:136 offset1:137
	v_pk_fma_f32 v[16:17], v[6:7], v[16:17], 0 op_sel_hi:[0,1,0]
	v_pk_fma_f32 v[16:17], v[2:3], v[22:23], v[16:17] op_sel_hi:[0,1,1]
	s_waitcnt lgkmcnt(3)
	v_pk_fma_f32 v[16:17], v[10:11], v[24:25], v[16:17] op_sel_hi:[0,1,1]
	s_waitcnt lgkmcnt(2)
	v_pk_fma_f32 v[16:17], v[4:5], v[26:27], v[16:17] op_sel_hi:[0,1,1]
	v_add_u32_e32 v3, 0x10800, v7
	v_add_u32_e32 v35, 0x18900, v7
	ds_read2st64_b32 v[22:23], v7 offset0:10 offset1:11
	ds_read2st64_b32 v[24:25], v7 offset0:12 offset1:13
	ds_read2st64_b32 v[26:27], v7 offset0:14 offset1:15
	s_waitcnt lgkmcnt(4)
	v_pk_fma_f32 v[18:19], v[6:7], v[18:19], 0 op_sel_hi:[0,1,0]
	v_add_u32_e32 v36, 0x10a00, v7
	v_add_u32_e32 v37, 0x18a00, v7
	v_add_u32_e32 v39, 0x10b00, v7
	v_add_u32_e32 v5, 0x18800, v7
	v_add_u32_e32 v11, 0x10900, v7
	ds_read2st64_b32 v[28:29], v7 offset0:138 offset1:139
	ds_read2st64_b32 v[30:31], v7 offset0:140 offset1:141
	ds_read2st64_b32 v[32:33], v7 offset0:142 offset1:143
	s_waitcnt lgkmcnt(6)
	v_pk_fma_f32 v[18:19], v[2:3], v[20:21], v[18:19] op_sel_hi:[0,1,1]
	v_add_u32_e32 v40, 0x18b00, v7
	ds_read_b32 v20, v3
	ds_read_b32 v34, v5
	ds_read_b32 v21, v11
	ds_read_b32 v35, v35
	ds_read_b32 v36, v36
	ds_read_b32 v38, v37
	ds_read_b32 v37, v39
	ds_read_b32 v39, v40
	s_waitcnt lgkmcnt(5)
	v_pk_fma_f32 v[18:19], v[10:11], v[20:21], v[18:19] op_sel_hi:[0,1,1]
	v_pk_fma_f32 v[20:21], v[6:7], v[22:23], 0 op_sel_hi:[0,1,0]
	v_pk_fma_f32 v[20:21], v[2:3], v[28:29], v[20:21] op_sel_hi:[0,1,1]
	v_add_u32_e32 v3, 0x10c00, v7
	v_pk_fma_f32 v[22:23], v[6:7], v[24:25], 0 op_sel_hi:[0,1,0]
	s_waitcnt lgkmcnt(4)
	v_pk_fma_f32 v[18:19], v[4:5], v[34:35], v[18:19] op_sel_hi:[0,1,1]
	s_waitcnt lgkmcnt(1)
	v_pk_fma_f32 v[20:21], v[10:11], v[36:37], v[20:21] op_sel_hi:[0,1,1]
	v_add_u32_e32 v29, 0x18d00, v7
	v_pk_fma_f32 v[22:23], v[2:3], v[30:31], v[22:23] op_sel_hi:[0,1,1]
	v_add_u32_e32 v30, 0x10e00, v7
	v_add_u32_e32 v31, 0x18e00, v7
	v_add_u32_e32 v35, 0x10f00, v7
	s_waitcnt lgkmcnt(0)
	v_pk_fma_f32 v[20:21], v[4:5], v[38:39], v[20:21] op_sel_hi:[0,1,1]
	v_add_u32_e32 v5, 0x18c00, v7
	v_add_u32_e32 v11, 0x10d00, v7
	v_add_u32_e32 v7, 0x18f00, v7
	ds_read_b32 v24, v3
	ds_read_b32 v28, v5
	ds_read_b32 v25, v11
	ds_read_b32 v29, v29
	ds_read_b32 v30, v30
	ds_read_b32 v34, v31
	ds_read_b32 v31, v35
	ds_read_b32 v35, v7
	v_pk_fma_f32 v[6:7], v[6:7], v[26:27], 0 op_sel_hi:[0,1,0]
	v_pk_fma_f32 v[2:3], v[2:3], v[32:33], v[6:7] op_sel_hi:[0,1,1]
	s_waitcnt lgkmcnt(5)
	v_pk_fma_f32 v[22:23], v[10:11], v[24:25], v[22:23] op_sel_hi:[0,1,1]
	s_waitcnt lgkmcnt(1)
	v_pk_fma_f32 v[2:3], v[10:11], v[30:31], v[2:3] op_sel_hi:[0,1,1]
	v_pk_fma_f32 v[22:23], v[4:5], v[28:29], v[22:23] op_sel_hi:[0,1,1]
	s_waitcnt lgkmcnt(0)
	v_pk_fma_f32 v[2:3], v[4:5], v[34:35], v[2:3] op_sel_hi:[0,1,1]
	v_pk_mul_f32 v[8:9], v[8:9], v[0:1] op_sel_hi:[1,0]
	v_pk_mul_f32 v[12:13], v[0:1], v[12:13] op_sel_hi:[0,1]
	v_pk_mul_f32 v[14:15], v[0:1], v[14:15] op_sel_hi:[0,1]
	v_pk_mul_f32 v[16:17], v[0:1], v[16:17] op_sel_hi:[0,1]
	v_pk_mul_f32 v[18:19], v[0:1], v[18:19] op_sel_hi:[0,1]
	v_pk_mul_f32 v[20:21], v[0:1], v[20:21] op_sel_hi:[0,1]
	v_pk_mul_f32 v[22:23], v[0:1], v[22:23] op_sel_hi:[0,1]
	v_pk_mul_f32 v[2:3], v[0:1], v[2:3] op_sel_hi:[0,1]
	v_lshlrev_b32_e32 v0, 11, v175
	v_lshl_or_b32 v0, v82, 16, v0
	v_lshlrev_b32_e32 v6, 5, v177
	v_lshl_add_u64 v[4:5], s[38:39], 0, v[0:1]
	v_ashrrev_i32_e32 v7, 31, v6
	v_lshl_add_u64 v[4:5], v[6:7], 1, v[4:5]
	v_mov_b32_e32 v177, v1
	v_lshl_add_u64 v[4:5], v[4:5], 0, v[176:177]
	s_mov_b64 s[4:5], 0x4328400
	v_lshl_add_u64 v[6:7], v[4:5], 0, s[4:5]
	s_mov_b32 s4, 0x4328000
	v_add_co_u32_e32 v4, vcc, s4, v4
	v_cvt_pk_bf16_f32 v8, v8, v9
	v_cvt_pk_bf16_f32 v9, v12, v13
	v_addc_co_u32_e32 v5, vcc, 0, v5, vcc
	global_store_dwordx2 v[4:5], v[8:9], off offset:1024
	v_cvt_pk_bf16_f32 v4, v14, v15
	v_cvt_pk_bf16_f32 v5, v16, v17
	global_store_dwordx2 v[6:7], v[4:5], off offset:16
	v_cvt_pk_bf16_f32 v4, v18, v19
	v_cvt_pk_bf16_f32 v5, v20, v21
	global_store_dwordx2 v[6:7], v[4:5], off offset:32
	v_cvt_pk_bf16_f32 v4, v22, v23
	v_cvt_pk_bf16_f32 v5, v2, v3
	global_store_dwordx2 v[6:7], v[4:5], off offset:48
	s_barrier
	s_mov_b64 s[14:15], 0
